# phase-1 epilogue rewritten by hand: one per-lane base address per tile + running scalar row offset, 16-byte pieces stored without cross-lane line pairing, RoPE sign applied by one packed multiply; on
# speedup vs baseline: 1.0211x; 1.0006x over previous
.LBB0_174:
	s_and_b64 vcc, exec, s[8:9]
	s_mov_b32 s10, s42
	s_mov_b32 s12, s44
	s_mov_b64 s[52:53], s[48:49]
	s_mov_b64 s[50:51], s[46:47]
	s_cbranch_vccnz .LBB0_275

.LBB0_178:
	ds_read_b128 v[148:151], v159
	ds_read_b128 v[152:155], v159 offset:1024
	ds_read_b128 v[164:167], v159 offset:2048
	ds_read_b128 v[168:171], v159 offset:3072
	s_add_u32 s52, s50, 0xfffc0080
	s_addc_u32 s53, s51, -1
	s_cmp_eq_u32 s92, 12
	s_cselect_b32 s55, s11, s53
	s_cselect_b32 s54, s13, s52
	s_cselect_b32 s53, s17, s91
	s_cselect_b32 s52, s43, s45
	v_lshl_add_u64 v[156:157], s[50:51], 0, v[140:141]
	s_add_i32 m0, s58, 0xc000
	ds_read_b128 v[172:175], v160
	ds_read_b128 v[176:179], v160 offset:1024
	ds_read_b128 v[180:183], v160 offset:2048
	ds_read_b128 v[184:187], v160 offset:3072
	ds_read_b128 v[188:191], v160 offset:4096
	ds_read_b128 v[196:199], v160 offset:5120
	ds_read_b128 v[200:203], v160 offset:6144
	ds_read_b128 v[204:207], v160 offset:7168
	global_load_lds_dwordx4 v[156:157], off
	v_lshl_add_u64 v[156:157], s[50:51], 0, v[142:143]
	s_add_i32 m0, s58, 0xe000
	s_nop 0
	global_load_lds_dwordx4 v[156:157], off
	s_waitcnt lgkmcnt(8)
	s_barrier
	s_waitcnt lgkmcnt(0)
	s_setprio 1
	s_waitcnt lgkmcnt(0)
	v_mfma_f32_16x16x32_bf16 v[124:127], v[148:151], v[172:175], v[124:127]
	v_mfma_f32_16x16x32_bf16 v[120:123], v[164:167], v[172:175], v[120:123]
	v_mfma_f32_16x16x32_bf16 v[108:111], v[148:151], v[180:183], v[108:111]
	v_mfma_f32_16x16x32_bf16 v[104:107], v[164:167], v[180:183], v[104:107]
	v_mfma_f32_16x16x32_bf16 v[92:95], v[148:151], v[188:191], v[92:95]
	v_mfma_f32_16x16x32_bf16 v[88:91], v[164:167], v[188:191], v[88:91]
	v_mfma_f32_16x16x32_bf16 v[76:79], v[148:151], v[200:203], v[76:79]
	v_mfma_f32_16x16x32_bf16 v[72:75], v[164:167], v[200:203], v[72:75]
	v_mfma_f32_16x16x32_bf16 v[124:127], v[152:155], v[176:179], v[124:127]
	v_mfma_f32_16x16x32_bf16 v[120:123], v[168:171], v[176:179], v[120:123]
	v_mfma_f32_16x16x32_bf16 v[108:111], v[152:155], v[184:187], v[108:111]
	v_mfma_f32_16x16x32_bf16 v[104:107], v[168:171], v[184:187], v[104:107]
	v_mfma_f32_16x16x32_bf16 v[92:95], v[152:155], v[196:199], v[92:95]
	v_mfma_f32_16x16x32_bf16 v[88:91], v[168:171], v[196:199], v[88:91]
	v_mfma_f32_16x16x32_bf16 v[76:79], v[152:155], v[204:207], v[76:79]
	v_mfma_f32_16x16x32_bf16 v[72:75], v[168:171], v[204:207], v[72:75]
	s_setprio 0
	s_barrier
	s_add_i32 s93, s89, s57
	v_lshl_add_u64 v[156:157], s[52:53], 0, v[130:131]
	s_mov_b32 m0, s93
	ds_read_b128 v[208:211], v161
	ds_read_b128 v[212:215], v161 offset:1024
	ds_read_b128 v[216:219], v161 offset:2048
	ds_read_b128 v[220:223], v161 offset:3072
	global_load_lds_dwordx4 v[156:157], off
	v_lshl_add_u64 v[224:225], s[52:53], 0, v[134:135]
	s_add_i32 m0, s93, 0x2000
	s_nop 0
	global_load_lds_dwordx4 v[224:225], off
	s_barrier
	s_waitcnt lgkmcnt(0)
	s_setprio 1
	s_waitcnt lgkmcnt(0)
	v_mfma_f32_16x16x32_bf16 v[116:119], v[208:211], v[172:175], v[116:119]
	v_mfma_f32_16x16x32_bf16 v[112:115], v[216:219], v[172:175], v[112:115]
	v_mfma_f32_16x16x32_bf16 v[100:103], v[208:211], v[180:183], v[100:103]
	v_mfma_f32_16x16x32_bf16 v[96:99], v[216:219], v[180:183], v[96:99]
	v_mfma_f32_16x16x32_bf16 v[84:87], v[208:211], v[188:191], v[84:87]
	v_mfma_f32_16x16x32_bf16 v[80:83], v[216:219], v[188:191], v[80:83]
	v_mfma_f32_16x16x32_bf16 v[68:71], v[208:211], v[200:203], v[68:71]
	v_mfma_f32_16x16x32_bf16 v[64:67], v[216:219], v[200:203], v[64:67]
	v_mfma_f32_16x16x32_bf16 v[116:119], v[212:215], v[176:179], v[116:119]
	v_mfma_f32_16x16x32_bf16 v[112:115], v[220:223], v[176:179], v[112:115]
	v_mfma_f32_16x16x32_bf16 v[100:103], v[212:215], v[184:187], v[100:103]
	v_mfma_f32_16x16x32_bf16 v[96:99], v[220:223], v[184:187], v[96:99]
	v_mfma_f32_16x16x32_bf16 v[84:87], v[212:215], v[196:199], v[84:87]
	v_mfma_f32_16x16x32_bf16 v[80:83], v[220:223], v[196:199], v[80:83]
	v_mfma_f32_16x16x32_bf16 v[68:71], v[212:215], v[204:207], v[68:71]
	v_mfma_f32_16x16x32_bf16 v[64:67], v[220:223], v[204:207], v[64:67]
	s_setprio 0
	s_mov_b32 m0, s58
	v_lshl_add_u64 v[226:227], s[54:55], 0, v[128:129]
	s_barrier
	ds_read_b128 v[172:175], v160 offset:16384
	ds_read_b128 v[176:179], v160 offset:17408
	ds_read_b128 v[180:183], v160 offset:18432
	ds_read_b128 v[184:187], v160 offset:19456
	ds_read_b128 v[188:191], v160 offset:20480
	ds_read_b128 v[196:199], v160 offset:21504
	ds_read_b128 v[200:203], v160 offset:22528
	ds_read_b128 v[204:207], v160 offset:23552
	global_load_lds_dwordx4 v[226:227], off
	v_lshl_add_u64 v[228:229], s[54:55], 0, v[132:133]
	s_mov_b32 m0, s59
	s_nop 0
	global_load_lds_dwordx4 v[228:229], off
	s_barrier
	s_waitcnt lgkmcnt(0)
	s_setprio 1
	s_waitcnt lgkmcnt(0)
	v_mfma_f32_16x16x32_bf16 v[60:63], v[148:151], v[172:175], v[60:63]
	v_mfma_f32_16x16x32_bf16 v[56:59], v[164:167], v[172:175], v[56:59]
	v_mfma_f32_16x16x32_bf16 v[44:47], v[148:151], v[180:183], v[44:47]
	v_mfma_f32_16x16x32_bf16 v[40:43], v[164:167], v[180:183], v[40:43]
	v_mfma_f32_16x16x32_bf16 v[28:31], v[148:151], v[188:191], v[28:31]
	v_mfma_f32_16x16x32_bf16 v[24:27], v[164:167], v[188:191], v[24:27]
	v_mfma_f32_16x16x32_bf16 v[12:15], v[148:151], v[200:203], v[12:15]
	v_mfma_f32_16x16x32_bf16 v[8:11], v[164:167], v[200:203], v[8:11]
	v_mfma_f32_16x16x32_bf16 v[60:63], v[152:155], v[176:179], v[60:63]
	v_mfma_f32_16x16x32_bf16 v[56:59], v[168:171], v[176:179], v[56:59]
	v_mfma_f32_16x16x32_bf16 v[44:47], v[152:155], v[184:187], v[44:47]
	v_mfma_f32_16x16x32_bf16 v[40:43], v[168:171], v[184:187], v[40:43]
	v_mfma_f32_16x16x32_bf16 v[28:31], v[152:155], v[196:199], v[28:31]
	v_mfma_f32_16x16x32_bf16 v[24:27], v[168:171], v[196:199], v[24:27]
	v_mfma_f32_16x16x32_bf16 v[12:15], v[152:155], v[204:207], v[12:15]
	v_mfma_f32_16x16x32_bf16 v[8:11], v[168:171], v[204:207], v[8:11]
	s_setprio 0
	s_barrier
	s_add_u32 s94, s52, 0x10000
	s_addc_u32 s95, s53, 0
	s_add_i32 s93, s90, s57
	v_lshl_add_u64 v[148:149], s[94:95], 0, v[130:131]
	s_mov_b32 m0, s93
	s_nop 0
	global_load_lds_dwordx4 v[148:149], off
	v_lshl_add_u64 v[148:149], s[94:95], 0, v[134:135]
	s_add_i32 m0, s93, 0x2000
	s_nop 0
	global_load_lds_dwordx4 v[148:149], off
	s_waitcnt vmcnt(6)
	s_barrier
	s_setprio 1
	v_mfma_f32_16x16x32_bf16 v[52:55], v[208:211], v[172:175], v[52:55]
	v_mfma_f32_16x16x32_bf16 v[48:51], v[216:219], v[172:175], v[48:51]
	v_mfma_f32_16x16x32_bf16 v[36:39], v[208:211], v[180:183], v[36:39]
	v_mfma_f32_16x16x32_bf16 v[32:35], v[216:219], v[180:183], v[32:35]
	v_mfma_f32_16x16x32_bf16 v[20:23], v[208:211], v[188:191], v[20:23]
	v_mfma_f32_16x16x32_bf16 v[16:19], v[216:219], v[188:191], v[16:19]
	v_mfma_f32_16x16x32_bf16 v[4:7], v[208:211], v[200:203], v[4:7]
	v_mfma_f32_16x16x32_bf16 v[0:3], v[216:219], v[200:203], v[0:3]
	v_mfma_f32_16x16x32_bf16 v[52:55], v[212:215], v[176:179], v[52:55]
	v_mfma_f32_16x16x32_bf16 v[48:51], v[220:223], v[176:179], v[48:51]
	v_mfma_f32_16x16x32_bf16 v[36:39], v[212:215], v[184:187], v[36:39]
	v_mfma_f32_16x16x32_bf16 v[32:35], v[220:223], v[184:187], v[32:35]
	v_mfma_f32_16x16x32_bf16 v[20:23], v[212:215], v[196:199], v[20:23]
	v_mfma_f32_16x16x32_bf16 v[16:19], v[220:223], v[196:199], v[16:19]
	v_mfma_f32_16x16x32_bf16 v[4:7], v[212:215], v[204:207], v[4:7]
	v_mfma_f32_16x16x32_bf16 v[0:3], v[220:223], v[204:207], v[0:3]
	s_setprio 0
	s_add_i32 s93, 0, 0x18000
	v_add_u32_e32 v136, s93, v158
	s_barrier
	ds_read_b128 v[148:151], v136
	ds_read_b128 v[152:155], v136 offset:1024
	ds_read_b128 v[164:167], v136 offset:2048
	ds_read_b128 v[168:171], v136 offset:3072
	s_add_u32 s54, s54, 0x40000
	s_addc_u32 s55, s55, 0
	s_mov_b32 m0, s60
	v_lshl_add_u64 v[208:209], s[54:55], 0, v[128:129]
	ds_read_b128 v[172:175], v160 offset:32768
	ds_read_b128 v[176:179], v160 offset:33792
	ds_read_b128 v[180:183], v160 offset:34816
	ds_read_b128 v[184:187], v160 offset:35840
	ds_read_b128 v[188:191], v160 offset:36864
	ds_read_b128 v[196:199], v160 offset:37888
	ds_read_b128 v[200:203], v160 offset:38912
	ds_read_b128 v[204:207], v160 offset:39936
	global_load_lds_dwordx4 v[208:209], off
	v_lshl_add_u64 v[208:209], s[54:55], 0, v[132:133]
	s_mov_b32 m0, s61
	s_nop 0
	global_load_lds_dwordx4 v[208:209], off
	s_waitcnt lgkmcnt(8)
	s_barrier
	s_waitcnt lgkmcnt(0)
	s_setprio 1
	s_waitcnt lgkmcnt(0)
	v_mfma_f32_16x16x32_bf16 v[124:127], v[148:151], v[172:175], v[124:127]
	v_mfma_f32_16x16x32_bf16 v[120:123], v[164:167], v[172:175], v[120:123]
	v_mfma_f32_16x16x32_bf16 v[108:111], v[148:151], v[180:183], v[108:111]
	v_mfma_f32_16x16x32_bf16 v[104:107], v[164:167], v[180:183], v[104:107]
	v_mfma_f32_16x16x32_bf16 v[92:95], v[148:151], v[188:191], v[92:95]
	v_mfma_f32_16x16x32_bf16 v[88:91], v[164:167], v[188:191], v[88:91]
	v_mfma_f32_16x16x32_bf16 v[76:79], v[148:151], v[200:203], v[76:79]
	v_mfma_f32_16x16x32_bf16 v[72:75], v[164:167], v[200:203], v[72:75]
	v_mfma_f32_16x16x32_bf16 v[124:127], v[152:155], v[176:179], v[124:127]
	v_mfma_f32_16x16x32_bf16 v[120:123], v[168:171], v[176:179], v[120:123]
	v_mfma_f32_16x16x32_bf16 v[108:111], v[152:155], v[184:187], v[108:111]
	v_mfma_f32_16x16x32_bf16 v[104:107], v[168:171], v[184:187], v[104:107]
	v_mfma_f32_16x16x32_bf16 v[92:95], v[152:155], v[196:199], v[92:95]
	v_mfma_f32_16x16x32_bf16 v[88:91], v[168:171], v[196:199], v[88:91]
	v_mfma_f32_16x16x32_bf16 v[76:79], v[152:155], v[204:207], v[76:79]
	v_mfma_f32_16x16x32_bf16 v[72:75], v[168:171], v[204:207], v[72:75]
	s_setprio 0
	s_barrier
	s_add_i32 s54, 0, 0x1c000
	s_add_i32 s55, s93, s57
	v_add_u32_e32 v136, s54, v158
	v_lshl_add_u64 v[156:157], v[156:157], 0, s[0:1]
	s_mov_b32 m0, s55
	ds_read_b128 v[208:211], v136
	ds_read_b128 v[212:215], v136 offset:1024
	ds_read_b128 v[216:219], v136 offset:2048
	ds_read_b128 v[220:223], v136 offset:3072
	global_load_lds_dwordx4 v[156:157], off
	v_lshl_add_u64 v[156:157], v[224:225], 0, s[0:1]
	s_add_i32 m0, s55, 0x2000
	s_nop 0
	global_load_lds_dwordx4 v[156:157], off
	s_barrier
	s_waitcnt lgkmcnt(0)
	s_setprio 1
	s_waitcnt lgkmcnt(0)
	v_mfma_f32_16x16x32_bf16 v[116:119], v[208:211], v[172:175], v[116:119]
	v_mfma_f32_16x16x32_bf16 v[112:115], v[216:219], v[172:175], v[112:115]
	v_mfma_f32_16x16x32_bf16 v[100:103], v[208:211], v[180:183], v[100:103]
	v_mfma_f32_16x16x32_bf16 v[96:99], v[216:219], v[180:183], v[96:99]
	v_mfma_f32_16x16x32_bf16 v[84:87], v[208:211], v[188:191], v[84:87]
	v_mfma_f32_16x16x32_bf16 v[80:83], v[216:219], v[188:191], v[80:83]
	v_mfma_f32_16x16x32_bf16 v[68:71], v[208:211], v[200:203], v[68:71]
	v_mfma_f32_16x16x32_bf16 v[64:67], v[216:219], v[200:203], v[64:67]
	v_mfma_f32_16x16x32_bf16 v[116:119], v[212:215], v[176:179], v[116:119]
	v_mfma_f32_16x16x32_bf16 v[112:115], v[220:223], v[176:179], v[112:115]
	v_mfma_f32_16x16x32_bf16 v[100:103], v[212:215], v[184:187], v[100:103]
	v_mfma_f32_16x16x32_bf16 v[96:99], v[220:223], v[184:187], v[96:99]
	v_mfma_f32_16x16x32_bf16 v[84:87], v[212:215], v[196:199], v[84:87]
	v_mfma_f32_16x16x32_bf16 v[80:83], v[220:223], v[196:199], v[80:83]
	v_mfma_f32_16x16x32_bf16 v[68:71], v[212:215], v[204:207], v[68:71]
	v_mfma_f32_16x16x32_bf16 v[64:67], v[220:223], v[204:207], v[64:67]
	s_setprio 0
	s_mov_b32 m0, s65
	v_lshl_add_u64 v[156:157], v[226:227], 0, s[0:1]
	s_barrier
	ds_read_b128 v[172:175], v160 offset:49152
	ds_read_b128 v[176:179], v160 offset:50176
	ds_read_b128 v[180:183], v160 offset:51200
	ds_read_b128 v[184:187], v160 offset:52224
	ds_read_b128 v[188:191], v160 offset:53248
	ds_read_b128 v[196:199], v160 offset:54272
	ds_read_b128 v[200:203], v160 offset:55296
	ds_read_b128 v[204:207], v160 offset:56320
	global_load_lds_dwordx4 v[156:157], off
	v_lshl_add_u64 v[156:157], v[228:229], 0, s[0:1]
	s_mov_b32 m0, s66
	s_nop 0
	global_load_lds_dwordx4 v[156:157], off
	s_barrier
	s_waitcnt lgkmcnt(0)
	s_setprio 1
	s_waitcnt lgkmcnt(0)
	v_mfma_f32_16x16x32_bf16 v[60:63], v[148:151], v[172:175], v[60:63]
	v_mfma_f32_16x16x32_bf16 v[56:59], v[164:167], v[172:175], v[56:59]
	v_mfma_f32_16x16x32_bf16 v[44:47], v[148:151], v[180:183], v[44:47]
	v_mfma_f32_16x16x32_bf16 v[40:43], v[164:167], v[180:183], v[40:43]
	v_mfma_f32_16x16x32_bf16 v[28:31], v[148:151], v[188:191], v[28:31]
	v_mfma_f32_16x16x32_bf16 v[24:27], v[164:167], v[188:191], v[24:27]
	v_mfma_f32_16x16x32_bf16 v[12:15], v[148:151], v[200:203], v[12:15]
	v_mfma_f32_16x16x32_bf16 v[8:11], v[164:167], v[200:203], v[8:11]
	v_mfma_f32_16x16x32_bf16 v[60:63], v[152:155], v[176:179], v[60:63]
	v_mfma_f32_16x16x32_bf16 v[56:59], v[168:171], v[176:179], v[56:59]
	v_mfma_f32_16x16x32_bf16 v[44:47], v[152:155], v[184:187], v[44:47]
	v_mfma_f32_16x16x32_bf16 v[40:43], v[168:171], v[184:187], v[40:43]
	v_mfma_f32_16x16x32_bf16 v[28:31], v[152:155], v[196:199], v[28:31]
	v_mfma_f32_16x16x32_bf16 v[24:27], v[168:171], v[196:199], v[24:27]
	v_mfma_f32_16x16x32_bf16 v[12:15], v[152:155], v[204:207], v[12:15]
	v_mfma_f32_16x16x32_bf16 v[8:11], v[168:171], v[204:207], v[8:11]
	s_setprio 0
	s_barrier
	s_add_u32 s52, s52, 0x10080
	s_addc_u32 s53, s53, 0
	s_add_i32 s54, s54, s57
	v_lshl_add_u64 v[148:149], s[52:53], 0, v[130:131]
	s_mov_b32 m0, s54
	s_nop 0
	global_load_lds_dwordx4 v[148:149], off
	v_lshl_add_u64 v[148:149], s[52:53], 0, v[134:135]
	s_add_i32 m0, s54, 0x2000
	s_nop 0
	global_load_lds_dwordx4 v[148:149], off
	s_waitcnt vmcnt(6)
	s_barrier
	s_setprio 1
	v_mfma_f32_16x16x32_bf16 v[52:55], v[208:211], v[172:175], v[52:55]
	v_mfma_f32_16x16x32_bf16 v[48:51], v[216:219], v[172:175], v[48:51]
	v_mfma_f32_16x16x32_bf16 v[36:39], v[208:211], v[180:183], v[36:39]
	v_mfma_f32_16x16x32_bf16 v[32:35], v[216:219], v[180:183], v[32:35]
	v_mfma_f32_16x16x32_bf16 v[20:23], v[208:211], v[188:191], v[20:23]
	v_mfma_f32_16x16x32_bf16 v[16:19], v[216:219], v[188:191], v[16:19]
	v_mfma_f32_16x16x32_bf16 v[4:7], v[208:211], v[200:203], v[4:7]
	v_mfma_f32_16x16x32_bf16 v[0:3], v[216:219], v[200:203], v[0:3]
	v_mfma_f32_16x16x32_bf16 v[52:55], v[212:215], v[176:179], v[52:55]
	v_mfma_f32_16x16x32_bf16 v[48:51], v[220:223], v[176:179], v[48:51]
	v_mfma_f32_16x16x32_bf16 v[36:39], v[212:215], v[184:187], v[36:39]
	v_mfma_f32_16x16x32_bf16 v[32:35], v[220:223], v[184:187], v[32:35]
	v_mfma_f32_16x16x32_bf16 v[20:23], v[212:215], v[196:199], v[20:23]
	v_mfma_f32_16x16x32_bf16 v[16:19], v[220:223], v[196:199], v[16:19]
	v_mfma_f32_16x16x32_bf16 v[4:7], v[212:215], v[204:207], v[4:7]
	v_mfma_f32_16x16x32_bf16 v[0:3], v[220:223], v[204:207], v[0:3]
	s_setprio 0
	s_add_i32 s92, s92, 2
	s_add_u32 s50, s50, 0x100
	s_addc_u32 s51, s51, 0
	s_add_u32 s45, s45, 0x100
	s_addc_u32 s91, s91, 0
	s_cmp_gt_u32 s92, 13
	s_barrier
	s_cbranch_scc0 .LBB0_178
	v_lshl_add_u32 v148, s12, 8, v139
	v_and_b32_e32 v149, 24, v138
	s_lshl_b32 s11, s10, 8
	s_or_b32 s11, s11, s87
	s_cmp_gt_i32 s10, 11
	s_cbranch_scc1 .Le1_gates
	s_lshr_b32 s13, s10, 1
	s_lshl_b32 s50, s13, 25
	s_add_u32 s50, s20, s50
	s_addc_u32 s51, s21, 0
	s_bfe_u32 s17, s11, 0x30006
	v_ashrrev_i32_e32 v150, 8, v148
	v_and_or_b32 v150, v150, -8, s17
	v_mov_b32_e32 v151, 0
	v_lshlrev_b64 v[150:151], 18, v[150:151]
	v_lshlrev_b32_e32 v136, 7, v148
	v_and_b32_e32 v136, 0x3ff80, v136
	v_lshl_add_u32 v136, v149, 1, v136
	v_lshl_add_u64 v[150:151], v[150:151], 0, v[136:137]
	v_lshl_add_u64 v[150:151], v[150:151], 0, s[50:51]
	s_movk_i32 s11, 0x800
	s_movk_i32 s17, 0x2800
	s_branch .Le1_addr
.Le1_gates:
	v_or_b32_e32 v136, s11, v149
	v_lshlrev_b32_e32 v136, 1, v136
	v_mov_b32_e32 v150, v148
	v_mov_b32_e32 v151, 0
	v_lshlrev_b64 v[150:151], 12, v[150:151]
	v_lshl_add_u64 v[150:151], v[150:151], 0, v[136:137]
	s_add_u32 s50, s38, s40
	s_addc_u32 s51, s39, s41
	v_lshl_add_u64 v[150:151], v[150:151], 0, s[50:51]
	s_mov_b32 s11, 0x10000
	s_mov_b32 s17, 0x50000
.Le1_addr:
	s_mov_b64 s[50:51], 0
	s_cmp_lt_i32 s10, 4
	s_cbranch_scc1 .Le1_rope
	v_cvt_pk_bf16_f32 v124, v124, v125
	v_cvt_pk_bf16_f32 v125, v126, v127
	v_cvt_pk_bf16_f32 v126, v120, v121
	v_cvt_pk_bf16_f32 v127, v122, v123
	v_cvt_pk_bf16_f32 v116, v116, v117
	v_cvt_pk_bf16_f32 v117, v118, v119
	v_cvt_pk_bf16_f32 v118, v112, v113
	v_cvt_pk_bf16_f32 v119, v114, v115
	v_lshl_add_u64 v[152:153], v[150:151], 0, s[50:51]
	global_store_dwordx4 v[152:153], v[124:127], off
	global_store_dwordx4 v[152:153], v[116:119], off offset:64
	s_add_u32 s50, s50, s11
	s_addc_u32 s51, s51, 0
	v_cvt_pk_bf16_f32 v108, v108, v109
	v_cvt_pk_bf16_f32 v109, v110, v111
	v_cvt_pk_bf16_f32 v110, v104, v105
	v_cvt_pk_bf16_f32 v111, v106, v107
	v_cvt_pk_bf16_f32 v100, v100, v101
	v_cvt_pk_bf16_f32 v101, v102, v103
	v_cvt_pk_bf16_f32 v102, v96, v97
	v_cvt_pk_bf16_f32 v103, v98, v99
	v_lshl_add_u64 v[154:155], v[150:151], 0, s[50:51]
	global_store_dwordx4 v[154:155], v[108:111], off
	global_store_dwordx4 v[154:155], v[100:103], off offset:64
	s_add_u32 s50, s50, s11
	s_addc_u32 s51, s51, 0
	v_cvt_pk_bf16_f32 v92, v92, v93
	v_cvt_pk_bf16_f32 v93, v94, v95
	v_cvt_pk_bf16_f32 v94, v88, v89
	v_cvt_pk_bf16_f32 v95, v90, v91
	v_cvt_pk_bf16_f32 v84, v84, v85
	v_cvt_pk_bf16_f32 v85, v86, v87
	v_cvt_pk_bf16_f32 v86, v80, v81
	v_cvt_pk_bf16_f32 v87, v82, v83
	v_lshl_add_u64 v[152:153], v[150:151], 0, s[50:51]
	global_store_dwordx4 v[152:153], v[92:95], off
	global_store_dwordx4 v[152:153], v[84:87], off offset:64
	s_add_u32 s50, s50, s11
	s_addc_u32 s51, s51, 0
	v_cvt_pk_bf16_f32 v76, v76, v77
	v_cvt_pk_bf16_f32 v77, v78, v79
	v_cvt_pk_bf16_f32 v78, v72, v73
	v_cvt_pk_bf16_f32 v79, v74, v75
	v_cvt_pk_bf16_f32 v68, v68, v69
	v_cvt_pk_bf16_f32 v69, v70, v71
	v_cvt_pk_bf16_f32 v70, v64, v65
	v_cvt_pk_bf16_f32 v71, v66, v67
	v_lshl_add_u64 v[154:155], v[150:151], 0, s[50:51]
	global_store_dwordx4 v[154:155], v[76:79], off
	global_store_dwordx4 v[154:155], v[68:71], off offset:64
	s_add_u32 s50, s50, s17
	s_addc_u32 s51, s51, 0
	v_cvt_pk_bf16_f32 v60, v60, v61
	v_cvt_pk_bf16_f32 v61, v62, v63
	v_cvt_pk_bf16_f32 v62, v56, v57
	v_cvt_pk_bf16_f32 v63, v58, v59
	v_cvt_pk_bf16_f32 v52, v52, v53
	v_cvt_pk_bf16_f32 v53, v54, v55
	v_cvt_pk_bf16_f32 v54, v48, v49
	v_cvt_pk_bf16_f32 v55, v50, v51
	v_lshl_add_u64 v[152:153], v[150:151], 0, s[50:51]
	global_store_dwordx4 v[152:153], v[60:63], off
	global_store_dwordx4 v[152:153], v[52:55], off offset:64
	s_add_u32 s50, s50, s11
	s_addc_u32 s51, s51, 0
	v_cvt_pk_bf16_f32 v44, v44, v45
	v_cvt_pk_bf16_f32 v45, v46, v47
	v_cvt_pk_bf16_f32 v46, v40, v41
	v_cvt_pk_bf16_f32 v47, v42, v43
	v_cvt_pk_bf16_f32 v36, v36, v37
	v_cvt_pk_bf16_f32 v37, v38, v39
	v_cvt_pk_bf16_f32 v38, v32, v33
	v_cvt_pk_bf16_f32 v39, v34, v35
	v_lshl_add_u64 v[154:155], v[150:151], 0, s[50:51]
	global_store_dwordx4 v[154:155], v[44:47], off
	global_store_dwordx4 v[154:155], v[36:39], off offset:64
	s_add_u32 s50, s50, s11
	s_addc_u32 s51, s51, 0
	v_cvt_pk_bf16_f32 v28, v28, v29
	v_cvt_pk_bf16_f32 v29, v30, v31
	v_cvt_pk_bf16_f32 v30, v24, v25
	v_cvt_pk_bf16_f32 v31, v26, v27
	v_cvt_pk_bf16_f32 v20, v20, v21
	v_cvt_pk_bf16_f32 v21, v22, v23
	v_cvt_pk_bf16_f32 v22, v16, v17
	v_cvt_pk_bf16_f32 v23, v18, v19
	v_lshl_add_u64 v[152:153], v[150:151], 0, s[50:51]
	global_store_dwordx4 v[152:153], v[28:31], off
	global_store_dwordx4 v[152:153], v[20:23], off offset:64
	s_add_u32 s50, s50, s11
	s_addc_u32 s51, s51, 0
	v_cvt_pk_bf16_f32 v12, v12, v13
	v_cvt_pk_bf16_f32 v13, v14, v15
	v_cvt_pk_bf16_f32 v14, v8, v9
	v_cvt_pk_bf16_f32 v15, v10, v11
	v_cvt_pk_bf16_f32 v4, v4, v5
	v_cvt_pk_bf16_f32 v5, v6, v7
	v_cvt_pk_bf16_f32 v6, v0, v1
	v_cvt_pk_bf16_f32 v7, v2, v3
	v_lshl_add_u64 v[154:155], v[150:151], 0, s[50:51]
	global_store_dwordx4 v[154:155], v[12:15], off
	global_store_dwordx4 v[154:155], v[4:7], off offset:64
	s_branch .LBB0_174
.Le1_rope:
	v_xor_b32_e32 v156, 16, v162
	v_lshlrev_b32_e32 v156, 2, v156
	v_mov_b32_e32 v164, 1.0
	v_cndmask_b32_e64 v164, v164, -1.0, s[4:5]
	v_lshlrev_b32_e32 v190, 6, v148
	s_and_saveexec_b64 s[12:13], s[2:3]
	global_load_dwordx4 v[196:199], v190, s[84:85] offset:32
	global_load_dwordx4 v[200:203], v190, s[84:85] offset:48
	global_load_dwordx4 v[204:207], v190, s[84:85]
	global_load_dwordx4 v[208:211], v190, s[84:85] offset:16
	v_add_u32_e32 v191, 0x400, v190
	global_load_dwordx4 v[212:215], v191, s[84:85] offset:32
	global_load_dwordx4 v[216:219], v191, s[84:85] offset:48
	global_load_dwordx4 v[220:223], v191, s[84:85]
	global_load_dwordx4 v[224:227], v191, s[84:85] offset:16
	v_add_u32_e32 v191, 0x800, v190
	global_load_dwordx4 v[228:231], v191, s[84:85] offset:32
	global_load_dwordx4 v[232:235], v191, s[84:85] offset:48
	global_load_dwordx4 v[236:239], v191, s[84:85]
	global_load_dwordx4 v[186:189], v191, s[84:85] offset:16
	s_or_b64 exec, exec, s[12:13]
	ds_bpermute_b32 v166, v156, v124
	ds_bpermute_b32 v167, v156, v125
	ds_bpermute_b32 v168, v156, v126
	ds_bpermute_b32 v169, v156, v127
	ds_bpermute_b32 v170, v156, v120
	ds_bpermute_b32 v171, v156, v121
	ds_bpermute_b32 v172, v156, v122
	ds_bpermute_b32 v173, v156, v123
	s_and_saveexec_b64 s[12:13], s[2:3]
	s_waitcnt vmcnt(8)
	v_pk_mul_f32 v[196:197], v[196:197], v[164:165] op_sel_hi:[1,0]
	v_pk_mul_f32 v[200:201], v[200:201], v[164:165] op_sel_hi:[1,0]
	v_pk_mul_f32 v[198:199], v[198:199], v[164:165] op_sel_hi:[1,0]
	v_pk_mul_f32 v[202:203], v[202:203], v[164:165] op_sel_hi:[1,0]
	s_waitcnt lgkmcnt(0)
	v_pk_mul_f32 v[166:167], v[196:197], v[166:167]
	v_pk_mul_f32 v[170:171], v[200:201], v[170:171]
	v_pk_mul_f32 v[168:169], v[198:199], v[168:169]
	v_pk_mul_f32 v[172:173], v[202:203], v[172:173]
	v_pk_fma_f32 v[124:125], v[124:125], v[204:205], v[166:167]
	v_pk_fma_f32 v[120:121], v[120:121], v[208:209], v[170:171]
	v_pk_fma_f32 v[126:127], v[126:127], v[206:207], v[168:169]
	v_pk_fma_f32 v[122:123], v[122:123], v[210:211], v[172:173]
	v_add_u32_e32 v191, 0xc00, v190
	global_load_dwordx4 v[196:199], v191, s[84:85] offset:32
	global_load_dwordx4 v[200:203], v191, s[84:85] offset:48
	global_load_dwordx4 v[204:207], v191, s[84:85]
	global_load_dwordx4 v[208:211], v191, s[84:85] offset:16
	s_or_b64 exec, exec, s[12:13]
	v_cvt_pk_bf16_f32 v124, v124, v125
	v_cvt_pk_bf16_f32 v125, v126, v127
	v_cvt_pk_bf16_f32 v126, v120, v121
	v_cvt_pk_bf16_f32 v127, v122, v123
	v_cvt_pk_bf16_f32 v116, v116, v117
	v_cvt_pk_bf16_f32 v117, v118, v119
	v_cvt_pk_bf16_f32 v118, v112, v113
	v_cvt_pk_bf16_f32 v119, v114, v115
	v_lshl_add_u64 v[152:153], v[150:151], 0, s[50:51]
	global_store_dwordx4 v[152:153], v[124:127], off
	global_store_dwordx4 v[152:153], v[116:119], off offset:64
	s_add_u32 s50, s50, s11
	s_addc_u32 s51, s51, 0
	ds_bpermute_b32 v166, v156, v108
	ds_bpermute_b32 v167, v156, v109
	ds_bpermute_b32 v168, v156, v110
	ds_bpermute_b32 v169, v156, v111
	ds_bpermute_b32 v170, v156, v104
	ds_bpermute_b32 v171, v156, v105
	ds_bpermute_b32 v172, v156, v106
	ds_bpermute_b32 v173, v156, v107
	s_and_saveexec_b64 s[12:13], s[2:3]
	s_waitcnt vmcnt(10)
	v_pk_mul_f32 v[212:213], v[212:213], v[164:165] op_sel_hi:[1,0]
	v_pk_mul_f32 v[216:217], v[216:217], v[164:165] op_sel_hi:[1,0]
	v_pk_mul_f32 v[214:215], v[214:215], v[164:165] op_sel_hi:[1,0]
	v_pk_mul_f32 v[218:219], v[218:219], v[164:165] op_sel_hi:[1,0]
	s_waitcnt lgkmcnt(0)
	v_pk_mul_f32 v[166:167], v[212:213], v[166:167]
	v_pk_mul_f32 v[170:171], v[216:217], v[170:171]
	v_pk_mul_f32 v[168:169], v[214:215], v[168:169]
	v_pk_mul_f32 v[172:173], v[218:219], v[172:173]
	v_pk_fma_f32 v[108:109], v[108:109], v[220:221], v[166:167]
	v_pk_fma_f32 v[104:105], v[104:105], v[224:225], v[170:171]
	v_pk_fma_f32 v[110:111], v[110:111], v[222:223], v[168:169]
	v_pk_fma_f32 v[106:107], v[106:107], v[226:227], v[172:173]
	v_add_u32_e32 v191, 0x2000, v190
	global_load_dwordx4 v[212:215], v191, s[84:85] offset:32
	global_load_dwordx4 v[216:219], v191, s[84:85] offset:48
	global_load_dwordx4 v[220:223], v191, s[84:85]
	global_load_dwordx4 v[224:227], v191, s[84:85] offset:16
	s_or_b64 exec, exec, s[12:13]
	v_cvt_pk_bf16_f32 v108, v108, v109
	v_cvt_pk_bf16_f32 v109, v110, v111
	v_cvt_pk_bf16_f32 v110, v104, v105
	v_cvt_pk_bf16_f32 v111, v106, v107
	v_cvt_pk_bf16_f32 v100, v100, v101
	v_cvt_pk_bf16_f32 v101, v102, v103
	v_cvt_pk_bf16_f32 v102, v96, v97
	v_cvt_pk_bf16_f32 v103, v98, v99
	v_lshl_add_u64 v[154:155], v[150:151], 0, s[50:51]
	global_store_dwordx4 v[154:155], v[108:111], off
	global_store_dwordx4 v[154:155], v[100:103], off offset:64
	s_add_u32 s50, s50, s11
	s_addc_u32 s51, s51, 0
	ds_bpermute_b32 v166, v156, v92
	ds_bpermute_b32 v167, v156, v93
	ds_bpermute_b32 v168, v156, v94
	ds_bpermute_b32 v169, v156, v95
	ds_bpermute_b32 v170, v156, v88
	ds_bpermute_b32 v171, v156, v89
	ds_bpermute_b32 v172, v156, v90
	ds_bpermute_b32 v173, v156, v91
	s_and_saveexec_b64 s[12:13], s[2:3]
	s_waitcnt vmcnt(12)
	v_pk_mul_f32 v[228:229], v[228:229], v[164:165] op_sel_hi:[1,0]
	v_pk_mul_f32 v[232:233], v[232:233], v[164:165] op_sel_hi:[1,0]
	v_pk_mul_f32 v[230:231], v[230:231], v[164:165] op_sel_hi:[1,0]
	v_pk_mul_f32 v[234:235], v[234:235], v[164:165] op_sel_hi:[1,0]
	s_waitcnt lgkmcnt(0)
	v_pk_mul_f32 v[166:167], v[228:229], v[166:167]
	v_pk_mul_f32 v[170:171], v[232:233], v[170:171]
	v_pk_mul_f32 v[168:169], v[230:231], v[168:169]
	v_pk_mul_f32 v[172:173], v[234:235], v[172:173]
	v_pk_fma_f32 v[92:93], v[92:93], v[236:237], v[166:167]
	v_pk_fma_f32 v[88:89], v[88:89], v[186:187], v[170:171]
	v_pk_fma_f32 v[94:95], v[94:95], v[238:239], v[168:169]
	v_pk_fma_f32 v[90:91], v[90:91], v[188:189], v[172:173]
	v_add_u32_e32 v191, 0x2400, v190
	global_load_dwordx4 v[228:231], v191, s[84:85] offset:32
	global_load_dwordx4 v[232:235], v191, s[84:85] offset:48
	global_load_dwordx4 v[236:239], v191, s[84:85]
	global_load_dwordx4 v[186:189], v191, s[84:85] offset:16
	s_or_b64 exec, exec, s[12:13]
	v_cvt_pk_bf16_f32 v92, v92, v93
	v_cvt_pk_bf16_f32 v93, v94, v95
	v_cvt_pk_bf16_f32 v94, v88, v89
	v_cvt_pk_bf16_f32 v95, v90, v91
	v_cvt_pk_bf16_f32 v84, v84, v85
	v_cvt_pk_bf16_f32 v85, v86, v87
	v_cvt_pk_bf16_f32 v86, v80, v81
	v_cvt_pk_bf16_f32 v87, v82, v83
	v_lshl_add_u64 v[152:153], v[150:151], 0, s[50:51]
	global_store_dwordx4 v[152:153], v[92:95], off
	global_store_dwordx4 v[152:153], v[84:87], off offset:64
	s_add_u32 s50, s50, s11
	s_addc_u32 s51, s51, 0
	ds_bpermute_b32 v166, v156, v76
	ds_bpermute_b32 v167, v156, v77
	ds_bpermute_b32 v168, v156, v78
	ds_bpermute_b32 v169, v156, v79
	ds_bpermute_b32 v170, v156, v72
	ds_bpermute_b32 v171, v156, v73
	ds_bpermute_b32 v172, v156, v74
	ds_bpermute_b32 v173, v156, v75
	s_and_saveexec_b64 s[12:13], s[2:3]
	s_waitcnt vmcnt(14)
	v_pk_mul_f32 v[196:197], v[196:197], v[164:165] op_sel_hi:[1,0]
	v_pk_mul_f32 v[200:201], v[200:201], v[164:165] op_sel_hi:[1,0]
	v_pk_mul_f32 v[198:199], v[198:199], v[164:165] op_sel_hi:[1,0]
	v_pk_mul_f32 v[202:203], v[202:203], v[164:165] op_sel_hi:[1,0]
	s_waitcnt lgkmcnt(0)
	v_pk_mul_f32 v[166:167], v[196:197], v[166:167]
	v_pk_mul_f32 v[170:171], v[200:201], v[170:171]
	v_pk_mul_f32 v[168:169], v[198:199], v[168:169]
	v_pk_mul_f32 v[172:173], v[202:203], v[172:173]
	v_pk_fma_f32 v[76:77], v[76:77], v[204:205], v[166:167]
	v_pk_fma_f32 v[72:73], v[72:73], v[208:209], v[170:171]
	v_pk_fma_f32 v[78:79], v[78:79], v[206:207], v[168:169]
	v_pk_fma_f32 v[74:75], v[74:75], v[210:211], v[172:173]
	v_add_u32_e32 v191, 0x2800, v190
	global_load_dwordx4 v[196:199], v191, s[84:85] offset:32
	global_load_dwordx4 v[200:203], v191, s[84:85] offset:48
	global_load_dwordx4 v[204:207], v191, s[84:85]
	global_load_dwordx4 v[208:211], v191, s[84:85] offset:16
	s_or_b64 exec, exec, s[12:13]
	v_cvt_pk_bf16_f32 v76, v76, v77
	v_cvt_pk_bf16_f32 v77, v78, v79
	v_cvt_pk_bf16_f32 v78, v72, v73
	v_cvt_pk_bf16_f32 v79, v74, v75
	v_cvt_pk_bf16_f32 v68, v68, v69
	v_cvt_pk_bf16_f32 v69, v70, v71
	v_cvt_pk_bf16_f32 v70, v64, v65
	v_cvt_pk_bf16_f32 v71, v66, v67
	v_lshl_add_u64 v[154:155], v[150:151], 0, s[50:51]
	global_store_dwordx4 v[154:155], v[76:79], off
	global_store_dwordx4 v[154:155], v[68:71], off offset:64
	s_add_u32 s50, s50, s17
	s_addc_u32 s51, s51, 0
	ds_bpermute_b32 v166, v156, v60
	ds_bpermute_b32 v167, v156, v61
	ds_bpermute_b32 v168, v156, v62
	ds_bpermute_b32 v169, v156, v63
	ds_bpermute_b32 v170, v156, v56
	ds_bpermute_b32 v171, v156, v57
	ds_bpermute_b32 v172, v156, v58
	ds_bpermute_b32 v173, v156, v59
	s_and_saveexec_b64 s[12:13], s[2:3]
	s_waitcnt vmcnt(14)
	v_pk_mul_f32 v[212:213], v[212:213], v[164:165] op_sel_hi:[1,0]
	v_pk_mul_f32 v[216:217], v[216:217], v[164:165] op_sel_hi:[1,0]
	v_pk_mul_f32 v[214:215], v[214:215], v[164:165] op_sel_hi:[1,0]
	v_pk_mul_f32 v[218:219], v[218:219], v[164:165] op_sel_hi:[1,0]
	s_waitcnt lgkmcnt(0)
	v_pk_mul_f32 v[166:167], v[212:213], v[166:167]
	v_pk_mul_f32 v[170:171], v[216:217], v[170:171]
	v_pk_mul_f32 v[168:169], v[214:215], v[168:169]
	v_pk_mul_f32 v[172:173], v[218:219], v[172:173]
	v_pk_fma_f32 v[60:61], v[60:61], v[220:221], v[166:167]
	v_pk_fma_f32 v[56:57], v[56:57], v[224:225], v[170:171]
	v_pk_fma_f32 v[62:63], v[62:63], v[222:223], v[168:169]
	v_pk_fma_f32 v[58:59], v[58:59], v[226:227], v[172:173]
	v_add_u32_e32 v191, 0x2c00, v190
	global_load_dwordx4 v[212:215], v191, s[84:85] offset:32
	global_load_dwordx4 v[216:219], v191, s[84:85] offset:48
	global_load_dwordx4 v[220:223], v191, s[84:85]
	global_load_dwordx4 v[224:227], v191, s[84:85] offset:16
	s_or_b64 exec, exec, s[12:13]
	v_cvt_pk_bf16_f32 v60, v60, v61
	v_cvt_pk_bf16_f32 v61, v62, v63
	v_cvt_pk_bf16_f32 v62, v56, v57
	v_cvt_pk_bf16_f32 v63, v58, v59
	v_cvt_pk_bf16_f32 v52, v52, v53
	v_cvt_pk_bf16_f32 v53, v54, v55
	v_cvt_pk_bf16_f32 v54, v48, v49
	v_cvt_pk_bf16_f32 v55, v50, v51
	v_lshl_add_u64 v[152:153], v[150:151], 0, s[50:51]
	global_store_dwordx4 v[152:153], v[60:63], off
	global_store_dwordx4 v[152:153], v[52:55], off offset:64
	s_add_u32 s50, s50, s11
	s_addc_u32 s51, s51, 0
	ds_bpermute_b32 v166, v156, v44
	ds_bpermute_b32 v167, v156, v45
	ds_bpermute_b32 v168, v156, v46
	ds_bpermute_b32 v169, v156, v47
	ds_bpermute_b32 v170, v156, v40
	ds_bpermute_b32 v171, v156, v41
	ds_bpermute_b32 v172, v156, v42
	ds_bpermute_b32 v173, v156, v43
	s_and_saveexec_b64 s[12:13], s[2:3]
	s_waitcnt vmcnt(14)
	v_pk_mul_f32 v[228:229], v[228:229], v[164:165] op_sel_hi:[1,0]
	v_pk_mul_f32 v[232:233], v[232:233], v[164:165] op_sel_hi:[1,0]
	v_pk_mul_f32 v[230:231], v[230:231], v[164:165] op_sel_hi:[1,0]
	v_pk_mul_f32 v[234:235], v[234:235], v[164:165] op_sel_hi:[1,0]
	s_waitcnt lgkmcnt(0)
	v_pk_mul_f32 v[166:167], v[228:229], v[166:167]
	v_pk_mul_f32 v[170:171], v[232:233], v[170:171]
	v_pk_mul_f32 v[168:169], v[230:231], v[168:169]
	v_pk_mul_f32 v[172:173], v[234:235], v[172:173]
	v_pk_fma_f32 v[44:45], v[44:45], v[236:237], v[166:167]
	v_pk_fma_f32 v[40:41], v[40:41], v[186:187], v[170:171]
	v_pk_fma_f32 v[46:47], v[46:47], v[238:239], v[168:169]
	v_pk_fma_f32 v[42:43], v[42:43], v[188:189], v[172:173]
	s_or_b64 exec, exec, s[12:13]
	v_cvt_pk_bf16_f32 v44, v44, v45
	v_cvt_pk_bf16_f32 v45, v46, v47
	v_cvt_pk_bf16_f32 v46, v40, v41
	v_cvt_pk_bf16_f32 v47, v42, v43
	v_cvt_pk_bf16_f32 v36, v36, v37
	v_cvt_pk_bf16_f32 v37, v38, v39
	v_cvt_pk_bf16_f32 v38, v32, v33
	v_cvt_pk_bf16_f32 v39, v34, v35
	v_lshl_add_u64 v[154:155], v[150:151], 0, s[50:51]
	global_store_dwordx4 v[154:155], v[44:47], off
	global_store_dwordx4 v[154:155], v[36:39], off offset:64
	s_add_u32 s50, s50, s11
	s_addc_u32 s51, s51, 0
	ds_bpermute_b32 v166, v156, v28
	ds_bpermute_b32 v167, v156, v29
	ds_bpermute_b32 v168, v156, v30
	ds_bpermute_b32 v169, v156, v31
	ds_bpermute_b32 v170, v156, v24
	ds_bpermute_b32 v171, v156, v25
	ds_bpermute_b32 v172, v156, v26
	ds_bpermute_b32 v173, v156, v27
	s_and_saveexec_b64 s[12:13], s[2:3]
	s_waitcnt vmcnt(10)
	v_pk_mul_f32 v[196:197], v[196:197], v[164:165] op_sel_hi:[1,0]
	v_pk_mul_f32 v[200:201], v[200:201], v[164:165] op_sel_hi:[1,0]
	v_pk_mul_f32 v[198:199], v[198:199], v[164:165] op_sel_hi:[1,0]
	v_pk_mul_f32 v[202:203], v[202:203], v[164:165] op_sel_hi:[1,0]
	s_waitcnt lgkmcnt(0)
	v_pk_mul_f32 v[166:167], v[196:197], v[166:167]
	v_pk_mul_f32 v[170:171], v[200:201], v[170:171]
	v_pk_mul_f32 v[168:169], v[198:199], v[168:169]
	v_pk_mul_f32 v[172:173], v[202:203], v[172:173]
	v_pk_fma_f32 v[28:29], v[28:29], v[204:205], v[166:167]
	v_pk_fma_f32 v[24:25], v[24:25], v[208:209], v[170:171]
	v_pk_fma_f32 v[30:31], v[30:31], v[206:207], v[168:169]
	v_pk_fma_f32 v[26:27], v[26:27], v[210:211], v[172:173]
	s_or_b64 exec, exec, s[12:13]
	v_cvt_pk_bf16_f32 v28, v28, v29
	v_cvt_pk_bf16_f32 v29, v30, v31
	v_cvt_pk_bf16_f32 v30, v24, v25
	v_cvt_pk_bf16_f32 v31, v26, v27
	v_cvt_pk_bf16_f32 v20, v20, v21
	v_cvt_pk_bf16_f32 v21, v22, v23
	v_cvt_pk_bf16_f32 v22, v16, v17
	v_cvt_pk_bf16_f32 v23, v18, v19
	v_lshl_add_u64 v[152:153], v[150:151], 0, s[50:51]
	global_store_dwordx4 v[152:153], v[28:31], off
	global_store_dwordx4 v[152:153], v[20:23], off offset:64
	s_add_u32 s50, s50, s11
	s_addc_u32 s51, s51, 0
	ds_bpermute_b32 v166, v156, v12
	ds_bpermute_b32 v167, v156, v13
	ds_bpermute_b32 v168, v156, v14
	ds_bpermute_b32 v169, v156, v15
	ds_bpermute_b32 v170, v156, v8
	ds_bpermute_b32 v171, v156, v9
	ds_bpermute_b32 v172, v156, v10
	ds_bpermute_b32 v173, v156, v11
	s_and_saveexec_b64 s[12:13], s[2:3]
	s_waitcnt vmcnt(6)
	v_pk_mul_f32 v[212:213], v[212:213], v[164:165] op_sel_hi:[1,0]
	v_pk_mul_f32 v[216:217], v[216:217], v[164:165] op_sel_hi:[1,0]
	v_pk_mul_f32 v[214:215], v[214:215], v[164:165] op_sel_hi:[1,0]
	v_pk_mul_f32 v[218:219], v[218:219], v[164:165] op_sel_hi:[1,0]
	s_waitcnt lgkmcnt(0)
	v_pk_mul_f32 v[166:167], v[212:213], v[166:167]
	v_pk_mul_f32 v[170:171], v[216:217], v[170:171]
	v_pk_mul_f32 v[168:169], v[214:215], v[168:169]
	v_pk_mul_f32 v[172:173], v[218:219], v[172:173]
	v_pk_fma_f32 v[12:13], v[12:13], v[220:221], v[166:167]
	v_pk_fma_f32 v[8:9], v[8:9], v[224:225], v[170:171]
	v_pk_fma_f32 v[14:15], v[14:15], v[222:223], v[168:169]
	v_pk_fma_f32 v[10:11], v[10:11], v[226:227], v[172:173]
	s_or_b64 exec, exec, s[12:13]
	v_cvt_pk_bf16_f32 v12, v12, v13
	v_cvt_pk_bf16_f32 v13, v14, v15
	v_cvt_pk_bf16_f32 v14, v8, v9
	v_cvt_pk_bf16_f32 v15, v10, v11
	v_cvt_pk_bf16_f32 v4, v4, v5
	v_cvt_pk_bf16_f32 v5, v6, v7
	v_cvt_pk_bf16_f32 v6, v0, v1
	v_cvt_pk_bf16_f32 v7, v2, v3
	v_lshl_add_u64 v[154:155], v[150:151], 0, s[50:51]
	global_store_dwordx4 v[154:155], v[12:15], off
	global_store_dwordx4 v[154:155], v[4:7], off offset:64
	s_branch .LBB0_174
